# T41: out-proj fused epilogue - second half's 16 residual row loads issued right after the first half's (into free v160-223), latency hidden behind first half's add/store stream
# speedup vs baseline: 1.0073x; 1.0073x over previous
; #define LAS __attribute__((address_space(3)))
; DI unsigned pk2(float lo, float hi) { f32x2 v = {lo, hi}; return __builtin_bit_cast(unsigned, __builtin_convertvector(v, bf2_t)); }
; DI int fresh_lane() { int l; asm volatile("v_mbcnt_lo_u32_b32 %0, -1, 0\n\tv_mbcnt_hi_u32_b32 %0, -1, %0" : "=v"(l)); return l; }
;     DI void fused(const f32x4 (&acc)[2][2][4][2], const pg8::Unit& u, int wr, int wc, LAS unsigned char* lds) const {
;         const int lane_ = fresh_lane(), fr = lane_ & 15, fq = lane_ >> 4;
;         const int w8 = wr * 4 + wc;
; #pragma unroll
;         for (int ai = 0; ai < 2; ++ai) {
; #pragma unroll
;             for (int m = 0; m < 4; ++m)
; #pragma unroll
;                 for (int bj = 0; bj < 2; ++bj)
; #pragma unroll
;                     for (int n = 0; n < 2; ++n)
;                         *(LAS f32x4*)(lds + (size_t)(wr * 64 + m * 16 + fr) * 1040 + (bj * 128 + wc * 32 + n * 16 + 4 * fq) * 4) = acc[ai][bj][m][n];
;             __syncthreads();
;             const size_t g0 = (size_t)(u.pm * 256 + ai * 128 + w8 * 16) * DM + u.pn * 256 + lane_ * 4;
;             f32x4 xo[16];
; #pragma unroll
;             for (int rr = 0; rr < 16; ++rr) xo[rr] = *(const f32x4*)(xin + g0 + (size_t)rr * DM);
; #pragma unroll
;             for (int rr = 0; rr < 16; ++rr) {
;                 const f32x4 a = *(const LAS f32x4*)(lds + (size_t)(w8 * 16 + rr) * 1040 + lane_ * 16);
;                 const f32x4 v = a + xo[rr];
;                 *(f32x4*)(xout + g0 + (size_t)rr * DM) = v;
;                 if (XB) {
;                     *(u32x2*)(XB + g0 + (size_t)rr * DM) = (u32x2){pk2(v[0], v[1]), pk2(v[2], v[3])};
;                     float part = (v[0] * v[0] + v[1] * v[1]) + (v[2] * v[2] + v[3] * v[3]);
;                     part = wave_sum(part, lane_);
;                     if (lane_ < 4) ssq_next[(size_t)(u.pm * 256 + ai * 128 + w8 * 16 + rr) * 16 + u.pn * 4 + lane_] = (lane_ == 0) ? part : 0.f;
;                 }
;             }
.LBB0_585:
	s_lshl_b32 s0, s62, 7
	s_waitcnt vmcnt(0)
	s_barrier
	v_mbcnt_lo_u32_b32 v130, -1, 0
	v_mbcnt_hi_u32_b32 v130, -1, v130
	s_add_i32 s0, s0, 0
	v_and_b32_e32 v131, -16, v130
	s_lshl_b32 s1, s62, 4
	v_add_u32_e32 v131, s0, v131
	s_lshl_b32 s0, s74, 8
	s_or_b32 s2, s1, s59
	s_add_i32 s18, s0, s2
	s_lshl_b32 s0, s73, 8
	v_lshlrev_b32_e32 v132, 2, v130
	s_ashr_i32 s1, s0, 31
	v_ashrrev_i32_e32 v133, 31, v132
	v_and_or_b32 v0, v130, 15, s59
	v_lshl_add_u64 v[132:133], v[132:133], 0, s[0:1]
	s_movk_i32 s0, 0x410
	s_ashr_i32 s19, s18, 31
	v_mul_lo_u32 v0, v0, s0
	s_lshl_b64 s[0:1], s[18:19], 10
	v_lshl_add_u64 v[140:141], v[132:133], 0, s[0:1]
	v_add_u32_e32 v138, v131, v0
	v_lshlrev_b64 v[142:143], 2, v[140:141]
	ds_write_b128 v138, v[126:129]
	ds_write_b128 v138, v[122:125] offset:64
	ds_write_b128 v138, v[118:121] offset:512
	ds_write_b128 v138, v[114:117] offset:576
	ds_write_b128 v138, v[110:113] offset:16640
	ds_write_b128 v138, v[106:109] offset:16704
	ds_write_b128 v138, v[102:105] offset:17152
	ds_write_b128 v138, v[98:101] offset:17216
	ds_write_b128 v138, v[94:97] offset:33280
	ds_write_b128 v138, v[90:93] offset:33344
	ds_write_b128 v138, v[86:89] offset:33792
	ds_write_b128 v138, v[82:85] offset:33856
	ds_write_b128 v138, v[78:81] offset:49920
	ds_write_b128 v138, v[74:77] offset:49984
	ds_write_b128 v138, v[70:73] offset:50432
	ds_write_b128 v138, v[66:69] offset:50496
	v_lshl_add_u64 v[66:67], s[14:15], 0, v[142:143]
	v_mov_b32_e32 v226, 0x80000
	v_mov_b32_e32 v227, 0
	v_lshl_add_u64 v[224:225], v[66:67], 0, v[226:227]
	v_mov_b32_e32 v226, 0x2000
	s_movk_i32 s80, 0x2000
	v_add_co_u32_e32 v68, vcc, s80, v66
	s_movk_i32 s81, 0x4000
	s_nop 0
	v_addc_co_u32_e32 v69, vcc, 0, v67, vcc
	s_waitcnt vmcnt(0) lgkmcnt(0)
	s_barrier
	global_load_dwordx4 v[126:129], v[66:67], off nt
	global_load_dwordx4 v[122:125], v[68:69], off offset:-4096 nt
	global_load_dwordx4 v[118:121], v[68:69], off nt
	v_add_co_u32_e32 v68, vcc, s81, v66
	s_movk_i32 s0, 0x6000
	s_nop 0
	v_addc_co_u32_e32 v69, vcc, 0, v67, vcc
	global_load_dwordx4 v[114:117], v[68:69], off offset:-4096 nt
	global_load_dwordx4 v[110:113], v[68:69], off nt
	v_add_co_u32_e32 v68, vcc, s0, v66
	s_mov_b32 s0, 0x8000
	s_nop 0
	v_addc_co_u32_e32 v69, vcc, 0, v67, vcc
	global_load_dwordx4 v[106:109], v[68:69], off offset:-4096 nt
	global_load_dwordx4 v[102:105], v[68:69], off nt
	v_add_co_u32_e32 v68, vcc, s0, v66
	s_mov_b32 s0, 0xa000
	s_nop 0
	v_addc_co_u32_e32 v69, vcc, 0, v67, vcc
	global_load_dwordx4 v[98:101], v[68:69], off offset:-4096 nt
	global_load_dwordx4 v[94:97], v[68:69], off nt
	v_add_co_u32_e32 v68, vcc, s0, v66
	s_mov_b32 s0, 0xc000
	s_nop 0
	v_addc_co_u32_e32 v69, vcc, 0, v67, vcc
	global_load_dwordx4 v[90:93], v[68:69], off offset:-4096 nt
	global_load_dwordx4 v[86:89], v[68:69], off nt
	v_add_co_u32_e32 v68, vcc, s0, v66
	s_mov_b32 s0, 0xe000
	s_nop 0
	v_addc_co_u32_e32 v69, vcc, 0, v67, vcc
	global_load_dwordx4 v[82:85], v[68:69], off offset:-4096 nt
	global_load_dwordx4 v[78:81], v[68:69], off nt
	v_add_co_u32_e32 v68, vcc, s0, v66
	s_mov_b32 s0, 0xf000
	s_nop 0
	v_addc_co_u32_e32 v69, vcc, 0, v67, vcc
	v_add_co_u32_e32 v66, vcc, s0, v66
	global_load_dwordx4 v[74:77], v[68:69], off offset:-4096 nt
	global_load_dwordx4 v[70:73], v[68:69], off nt
	v_addc_co_u32_e32 v67, vcc, 0, v67, vcc
	global_load_dwordx4 v[66:69], v[66:67], off nt
	global_load_dwordx4 v[160:163], v[224:225], off nt
	v_lshl_add_u64 v[224:225], v[224:225], 0, v[226:227]
	global_load_dwordx4 v[164:167], v[224:225], off offset:-4096 nt
	global_load_dwordx4 v[168:171], v[224:225], off nt
	v_lshl_add_u64 v[224:225], v[224:225], 0, v[226:227]
	global_load_dwordx4 v[172:175], v[224:225], off offset:-4096 nt
	global_load_dwordx4 v[176:179], v[224:225], off nt
	v_lshl_add_u64 v[224:225], v[224:225], 0, v[226:227]
	global_load_dwordx4 v[180:183], v[224:225], off offset:-4096 nt
	global_load_dwordx4 v[184:187], v[224:225], off nt
	v_lshl_add_u64 v[224:225], v[224:225], 0, v[226:227]
	global_load_dwordx4 v[188:191], v[224:225], off offset:-4096 nt
	global_load_dwordx4 v[192:195], v[224:225], off nt
	v_lshl_add_u64 v[224:225], v[224:225], 0, v[226:227]
	global_load_dwordx4 v[196:199], v[224:225], off offset:-4096 nt
	global_load_dwordx4 v[200:203], v[224:225], off nt
	v_lshl_add_u64 v[224:225], v[224:225], 0, v[226:227]
	global_load_dwordx4 v[204:207], v[224:225], off offset:-4096 nt
	global_load_dwordx4 v[208:211], v[224:225], off nt
	v_lshl_add_u64 v[224:225], v[224:225], 0, v[226:227]
	global_load_dwordx4 v[212:215], v[224:225], off offset:-4096 nt
	global_load_dwordx4 v[216:219], v[224:225], off nt
	v_mov_b32_e32 v226, 0x1000
	v_lshl_add_u64 v[224:225], v[224:225], 0, v[226:227]
	global_load_dwordx4 v[220:223], v[224:225], off nt
	v_lshl_add_u32 v0, v130, 4, 0
	s_mulk_i32 s2, 0x410
	v_add_u32_e32 v0, s2, v0
	ds_read_b128 v[134:137], v0
	s_lshl_b32 s16, s73, 2
	s_mov_b32 s86, s60
	v_readlane_b32 s60, v255, 52
	v_cmp_gt_i32_e64 s[4:5], 4, v130
	v_cmp_eq_u32_e64 s[0:1], 0, v130
	s_ashr_i32 s17, s16, 31
	v_ashrrev_i32_e32 v131, 31, v130
	s_andn2_b64 vcc, exec, s[8:9]
	s_mov_b32 s97, s94
	v_readlane_b32 s37, v255, 51
	v_readlane_b32 s61, v255, 53
	s_waitcnt vmcnt(31) lgkmcnt(0)
	v_pk_add_f32 v[126:127], v[126:127], v[134:135]
	v_cndmask_b32_e64 v134, 0, 1, s[8:9]
	v_pk_add_f32 v[128:129], v[128:129], v[136:137]
	v_lshl_add_u64 v[136:137], s[48:49], 0, v[142:143]
	v_cmp_ne_u32_e64 s[6:7], 1, v134
	v_lshl_add_u64 v[134:135], v[140:141], 1, s[12:13]
	global_store_dwordx4 v[136:137], v[126:129], off nt
	s_cbranch_vccnz .LBB0_589
	v_cvt_pk_bf16_f32 v140, v126, v127
	v_mul_f32_e32 v127, v127, v127
	v_fmac_f32_e32 v127, v126, v126
	v_mul_f32_e32 v126, v129, v129
	v_fmac_f32_e32 v126, v128, v128
	v_add_f32_e32 v126, v127, v126
	v_cvt_pk_bf16_f32 v141, v128, v129
	flat_store_dwordx2 v[134:135], v[140:141]
	v_add_f32_dpp v126, v126, v126 row_ror:1 row_mask:0xf bank_mask:0xf bound_ctrl:1
	s_nop 1
	v_add_f32_dpp v126, v126, v126 row_ror:2 row_mask:0xf bank_mask:0xf bound_ctrl:1
	s_nop 1
	v_add_f32_dpp v126, v126, v126 row_ror:4 row_mask:0xf bank_mask:0xf bound_ctrl:1
	s_nop 1
	v_add_f32_dpp v126, v126, v126 row_ror:8 row_mask:0xf bank_mask:0xf bound_ctrl:1
	s_nop 0
	v_readlane_b32 s24, v126, 0
	v_readlane_b32 s2, v126, 16
	v_readlane_b32 s25, v126, 32
	v_readlane_b32 s3, v126, 48
	s_and_saveexec_b64 s[22:23], s[4:5]
	s_cbranch_execz .LBB0_588
	v_mov_b32_e32 v126, s2
	v_mov_b32_e32 v127, s3
	s_lshl_b64 s[2:3], s[18:19], 6
	s_add_u32 s19, s10, s2
	s_addc_u32 s20, s11, s3
	s_lshl_b64 s[2:3], s[16:17], 2
	v_pk_add_f32 v[126:127], s[24:25], v[126:127]
	s_add_u32 s2, s19, s2
	v_add_f32_e32 v126, v126, v127
	s_addc_u32 s3, s20, s3
	v_cndmask_b32_e64 v128, 0, v126, s[0:1]
	v_lshl_add_u64 v[126:127], v[130:131], 2, s[2:3]
	flat_store_dword v[126:127], v128

; #define LAS __attribute__((address_space(3)))
; DI unsigned pk2(float lo, float hi) { f32x2 v = {lo, hi}; return __builtin_bit_cast(unsigned, __builtin_convertvector(v, bf2_t)); }
;     DI void fused(const f32x4 (&acc)[2][2][4][2], const pg8::Unit& u, int wr, int wc, LAS unsigned char* lds) const {
;     ...
;             for (int rr = 0; rr < 16; ++rr) {
;                 const f32x4 a = *(const LAS f32x4*)(lds + (size_t)(w8 * 16 + rr) * 1040 + lane_ * 16);
;                 const f32x4 v = a + xo[rr];
;                 *(f32x4*)(xout + g0 + (size_t)rr * DM) = v;
;                 if (XB) {
;                     *(u32x2*)(XB + g0 + (size_t)rr * DM) = (u32x2){pk2(v[0], v[1]), pk2(v[2], v[3])};
;                     float part = (v[0] * v[0] + v[1] * v[1]) + (v[2] * v[2] + v[3] * v[3]);
;                     part = wave_sum(part, lane_);
;                     if (lane_ < 4) ssq_next[(size_t)(u.pm * 256 + ai * 128 + w8 * 16 + rr) * 16 + u.pn * 4 + lane_] = (lane_ == 0) ? part : 0.f;
;                 }
.LBB0_589:
	ds_read_b128 v[126:129], v0 offset:1040
	s_waitcnt vmcnt(16) lgkmcnt(0)
	v_pk_add_f32 v[122:123], v[122:123], v[126:127]
	v_add_co_u32_e32 v126, vcc, 0x1000, v136
	v_pk_add_f32 v[124:125], v[124:125], v[128:129]
	s_nop 0
	v_addc_co_u32_e32 v127, vcc, 0, v137, vcc
	s_and_b64 vcc, exec, s[6:7]
	global_store_dwordx4 v[126:127], v[122:125], off nt
	s_cbranch_vccnz .LBB0_593
	v_cvt_pk_bf16_f32 v126, v122, v123
	v_mul_f32_e32 v123, v123, v123
	v_fmac_f32_e32 v123, v122, v122
	v_mul_f32_e32 v122, v125, v125
	v_fmac_f32_e32 v122, v124, v124
	v_add_f32_e32 v122, v123, v122
	v_cvt_pk_bf16_f32 v127, v124, v125
	flat_store_dwordx2 v[134:135], v[126:127] offset:2048
	v_add_f32_dpp v122, v122, v122 row_ror:1 row_mask:0xf bank_mask:0xf bound_ctrl:1
	s_nop 1
	v_add_f32_dpp v122, v122, v122 row_ror:2 row_mask:0xf bank_mask:0xf bound_ctrl:1
	s_nop 1
	v_add_f32_dpp v122, v122, v122 row_ror:4 row_mask:0xf bank_mask:0xf bound_ctrl:1
	s_nop 1
	v_add_f32_dpp v122, v122, v122 row_ror:8 row_mask:0xf bank_mask:0xf bound_ctrl:1
	s_nop 0
	v_readlane_b32 s24, v122, 0
	v_readlane_b32 s2, v122, 16
	v_readlane_b32 s25, v122, 32
	v_readlane_b32 s3, v122, 48
	s_and_saveexec_b64 s[22:23], s[4:5]
	s_cbranch_execz .LBB0_592
	v_mov_b32_e32 v122, s2
	s_or_b32 s2, s18, 1
	v_mov_b32_e32 v123, s3
	s_ashr_i32 s3, s2, 31
	s_lshl_b64 s[2:3], s[2:3], 6
	s_add_u32 s19, s10, s2
	s_addc_u32 s20, s11, s3
	s_lshl_b64 s[2:3], s[16:17], 2
	v_pk_add_f32 v[122:123], s[24:25], v[122:123]
	s_add_u32 s2, s19, s2
	v_add_f32_e32 v122, v122, v123
	s_addc_u32 s3, s20, s3
	v_cndmask_b32_e64 v124, 0, v122, s[0:1]
	v_lshl_add_u64 v[122:123], v[130:131], 2, s[2:3]
	flat_store_dword v[122:123], v124

; #define LAS __attribute__((address_space(3)))
;     DI void fused(const f32x4 (&acc)[2][2][4][2], const pg8::Unit& u, int wr, int wc, LAS unsigned char* lds) const {
;     ...
;         for (int ai = 0; ai < 2; ++ai) {
; #pragma unroll
;             for (int m = 0; m < 4; ++m)
; #pragma unroll
;                 for (int bj = 0; bj < 2; ++bj)
; #pragma unroll
;                     for (int n = 0; n < 2; ++n)
;                         *(LAS f32x4*)(lds + (size_t)(wr * 64 + m * 16 + fr) * 1040 + (bj * 128 + wc * 32 + n * 16 + 4 * fq) * 4) = acc[ai][bj][m][n];
;             __syncthreads();
;             const size_t g0 = (size_t)(u.pm * 256 + ai * 128 + w8 * 16) * DM + u.pn * 256 + lane_ * 4;
;             f32x4 xo[16];
; #pragma unroll
;             for (int rr = 0; rr < 16; ++rr) xo[rr] = *(const f32x4*)(xin + g0 + (size_t)rr * DM);
; #pragma unroll
;             for (int rr = 0; rr < 16; ++rr) {
;                 const f32x4 a = *(const LAS f32x4*)(lds + (size_t)(w8 * 16 + rr) * 1040 + lane_ * 16);
;                 const f32x4 v = a + xo[rr];
;                 *(f32x4*)(xout + g0 + (size_t)rr * DM) = v;
.LBB0_649:
	s_addk_i32 s18, 0x80
	s_ashr_i32 s19, s18, 31
	s_lshl_b64 s[2:3], s[18:19], 10
	v_lshl_add_u64 v[72:73], v[132:133], 0, s[2:3]
	v_lshlrev_b64 v[66:67], 2, v[72:73]
	s_waitcnt lgkmcnt(0)
	s_barrier
	ds_write_b128 v138, v[62:65]
	ds_write_b128 v138, v[58:61] offset:64
	ds_write_b128 v138, v[54:57] offset:512
	ds_write_b128 v138, v[50:53] offset:576
	ds_write_b128 v138, v[46:49] offset:16640
	ds_write_b128 v138, v[42:45] offset:16704
	ds_write_b128 v138, v[38:41] offset:17152
	ds_write_b128 v138, v[34:37] offset:17216
	ds_write_b128 v138, v[30:33] offset:33280
	ds_write_b128 v138, v[26:29] offset:33344
	ds_write_b128 v138, v[22:25] offset:33792
	ds_write_b128 v138, v[18:21] offset:33856
	ds_write_b128 v138, v[14:17] offset:49920
	ds_write_b128 v138, v[10:13] offset:49984
	ds_write_b128 v138, v[6:9] offset:50432
	ds_write_b128 v138, v[2:5] offset:50496
	v_lshl_add_u64 v[2:3], s[14:15], 0, v[66:67]
	v_add_co_u32_e32 v4, vcc, s80, v2
	s_waitcnt lgkmcnt(0)
	s_nop 0
	v_addc_co_u32_e32 v5, vcc, 0, v3, vcc
	s_barrier
	s_waitcnt vmcnt(0)
	v_mov_b64_e32 v[62:63], v[160:161]
	v_mov_b64_e32 v[64:65], v[162:163]
	v_mov_b64_e32 v[58:59], v[164:165]
	v_mov_b64_e32 v[60:61], v[166:167]
	v_mov_b64_e32 v[54:55], v[168:169]
	v_mov_b64_e32 v[56:57], v[170:171]
	v_add_co_u32_e32 v4, vcc, s81, v2
	s_movk_i32 s2, 0x6000
	s_nop 0
	v_addc_co_u32_e32 v5, vcc, 0, v3, vcc
	v_mov_b64_e32 v[50:51], v[172:173]
	v_mov_b64_e32 v[52:53], v[174:175]
	v_mov_b64_e32 v[46:47], v[176:177]
	v_mov_b64_e32 v[48:49], v[178:179]
	v_add_co_u32_e32 v4, vcc, s2, v2
	s_mov_b32 s2, 0x8000
	s_nop 0
	v_addc_co_u32_e32 v5, vcc, 0, v3, vcc
	v_mov_b64_e32 v[42:43], v[180:181]
	v_mov_b64_e32 v[44:45], v[182:183]
	v_mov_b64_e32 v[38:39], v[184:185]
	v_mov_b64_e32 v[40:41], v[186:187]
	v_add_co_u32_e32 v4, vcc, s2, v2
	s_mov_b32 s2, 0xa000
	s_nop 0
	v_addc_co_u32_e32 v5, vcc, 0, v3, vcc
	v_mov_b64_e32 v[34:35], v[188:189]
	v_mov_b64_e32 v[36:37], v[190:191]
	v_mov_b64_e32 v[30:31], v[192:193]
	v_mov_b64_e32 v[32:33], v[194:195]
	v_add_co_u32_e32 v4, vcc, s2, v2
	s_mov_b32 s2, 0xc000
	s_nop 0
	v_addc_co_u32_e32 v5, vcc, 0, v3, vcc
	v_mov_b64_e32 v[26:27], v[196:197]
	v_mov_b64_e32 v[28:29], v[198:199]
	v_mov_b64_e32 v[22:23], v[200:201]
	v_mov_b64_e32 v[24:25], v[202:203]
	v_add_co_u32_e32 v4, vcc, s2, v2
	s_mov_b32 s2, 0xe000
	s_nop 0
	v_addc_co_u32_e32 v5, vcc, 0, v3, vcc
	v_mov_b64_e32 v[18:19], v[204:205]
	v_mov_b64_e32 v[20:21], v[206:207]
	v_mov_b64_e32 v[14:15], v[208:209]
	v_mov_b64_e32 v[16:17], v[210:211]
	v_add_co_u32_e32 v4, vcc, s2, v2
	s_mov_b32 s2, 0xf000
	s_nop 0
	v_addc_co_u32_e32 v5, vcc, 0, v3, vcc
	v_add_co_u32_e32 v2, vcc, s2, v2
	v_mov_b64_e32 v[10:11], v[212:213]
	v_mov_b64_e32 v[12:13], v[214:215]
	v_mov_b64_e32 v[6:7], v[216:217]
	v_mov_b64_e32 v[8:9], v[218:219]
	v_addc_co_u32_e32 v3, vcc, 0, v3, vcc
	v_mov_b64_e32 v[2:3], v[220:221]
	v_mov_b64_e32 v[4:5], v[222:223]
	ds_read_b128 v[68:71], v0
	s_mov_b64 s[14:15], -1
	v_lshl_add_u64 v[66:67], s[48:49], 0, v[66:67]
	s_and_b64 vcc, exec, s[6:7]
	s_waitcnt vmcnt(0) lgkmcnt(0)
	v_pk_add_f32 v[64:65], v[64:65], v[70:71]
	v_pk_add_f32 v[62:63], v[62:63], v[68:69]
	v_lshl_add_u64 v[68:69], v[72:73], 1, s[12:13]
	global_store_dwordx4 v[66:67], v[62:65], off nt
	s_cbranch_vccnz .LBB0_655
	v_cvt_pk_bf16_f32 v70, v62, v63
	v_mul_f32_e32 v63, v63, v63
	v_fmac_f32_e32 v63, v62, v62
	v_mul_f32_e32 v62, v65, v65
	v_fmac_f32_e32 v62, v64, v64
	v_add_f32_e32 v62, v63, v62
	v_cvt_pk_bf16_f32 v71, v64, v65
	flat_store_dwordx2 v[68:69], v[70:71]
	v_add_f32_dpp v62, v62, v62 row_ror:1 row_mask:0xf bank_mask:0xf bound_ctrl:1
	s_nop 1
	v_add_f32_dpp v62, v62, v62 row_ror:2 row_mask:0xf bank_mask:0xf bound_ctrl:1
	s_nop 1
	v_add_f32_dpp v62, v62, v62 row_ror:4 row_mask:0xf bank_mask:0xf bound_ctrl:1
	s_nop 1
	v_add_f32_dpp v62, v62, v62 row_ror:8 row_mask:0xf bank_mask:0xf bound_ctrl:1
	s_nop 0
	v_readlane_b32 s14, v62, 0
	v_readlane_b32 s2, v62, 16
	v_readlane_b32 s15, v62, 32
	v_readlane_b32 s3, v62, 48
	s_and_saveexec_b64 s[12:13], s[4:5]
	s_cbranch_execz .LBB0_652
	v_mov_b32_e32 v62, s2
	v_mov_b32_e32 v63, s3
	s_lshl_b64 s[2:3], s[18:19], 6
	v_pk_add_f32 v[62:63], s[14:15], v[62:63]
	s_add_u32 s14, s10, s2
	s_addc_u32 s15, s11, s3
	s_lshl_b64 s[2:3], s[16:17], 2
	s_add_u32 s2, s14, s2
	v_add_f32_e32 v62, v62, v63
	s_addc_u32 s3, s15, s3
	v_cndmask_b32_e64 v64, 0, v62, s[0:1]
	v_lshl_add_u64 v[62:63], v[130:131], 2, s[2:3]
	flat_store_dword v[62:63], v64
